# last deferred epilogue piece moved from load segment into MFMA block 2, rowss prefetch one segment later
# speedup vs baseline: 1.0181x; 1.0181x over previous
.Lmy_b16_pdefer:
	s_add_u32 s1, s12, 0xfffc0080
	s_addc_u32 s14, s13, -1
	s_add_i32 s33, 0, 0x10000
	s_cmp_eq_u32 s73, 12
	s_cselect_b32 s29, s11, s14
	s_cselect_b32 s28, s30, s1
	v_add_u32_e32 v100, s33, v154
	s_cselect_b32 s15, s31, s55
	s_cselect_b32 s14, s47, s54
	s_add_i32 s1, 0, 0x14000
	ds_read_b128 v[144:147], v100
	ds_read_b128 v[148:151], v100 offset:1024
	ds_read_b128 v[158:161], v100 offset:2048
	ds_read_b128 v[162:165], v100 offset:3072
	v_add_u32_e32 v100, s1, v154
	ds_read_b128 v[166:169], v100
	ds_read_b128 v[170:173], v100 offset:1024
	ds_read_b128 v[174:177], v100 offset:2048
	ds_read_b128 v[178:181], v100 offset:3072
	v_lshl_add_u64 v[152:153], s[12:13], 0, v[140:141]
	s_add_i32 m0, s41, 0xc000
	ds_read_b128 v[182:185], v156
	ds_read_b128 v[186:189], v156 offset:1024
	ds_read_b128 v[190:193], v156 offset:2048
	ds_read_b128 v[194:197], v156 offset:3072
	ds_read_b128 v[198:201], v156 offset:4096
	ds_read_b128 v[202:205], v156 offset:5120
	ds_read_b128 v[208:211], v156 offset:6144
	ds_read_b128 v[226:229], v156 offset:7168
	global_load_lds_dwordx4 v[152:153], off
	v_lshl_add_u64 v[152:153], s[12:13], 0, v[142:143]
	s_add_i32 m0, s41, 0xe000
	s_nop 0
	global_load_lds_dwordx4 v[152:153], off
	v_and_b32_e32 v100, 3, v224
	v_lshlrev_b32_e32 v100, 6, v100
	v_and_or_b32 v100, v224, 60, v100
	v_mov_b32_e32 v152, v247
	v_fmamk_f32 v234, v236, 0x3a800000, v207
	v_rsq_f32_e32 v234, v234
	s_nop 0
	v_mul_f32_e32 v234, s36, v234
	v_pk_mul_f32 v[126:127], v[126:127], v[234:235] op_sel_hi:[1,0]
	v_pk_mul_f32 v[128:129], v[128:129], v[234:235] op_sel_hi:[1,0]
	v_pk_mul_f32 v[122:123], v[122:123], v[234:235] op_sel_hi:[1,0]
	v_pk_mul_f32 v[124:125], v[124:125], v[234:235] op_sel_hi:[1,0]
	v_cvt_pk_bf16_f32 v126, v126, v127
	v_cvt_pk_bf16_f32 v127, v128, v129
	v_cvt_pk_bf16_f32 v128, v122, v123
	v_cvt_pk_bf16_f32 v129, v124, v125
	ds_bpermute_b32 v122, v100, v126
	ds_bpermute_b32 v123, v100, v127
	ds_bpermute_b32 v124, v100, v128
	ds_bpermute_b32 v125, v100, v129
	v_fmamk_f32 v234, v237, 0x3a800000, v207
	v_rsq_f32_e32 v234, v234
	s_nop 0
	v_mul_f32_e32 v234, s36, v234
	v_pk_mul_f32 v[110:111], v[110:111], v[234:235] op_sel_hi:[1,0]
	v_pk_mul_f32 v[112:113], v[112:113], v[234:235] op_sel_hi:[1,0]
	v_pk_mul_f32 v[106:107], v[106:107], v[234:235] op_sel_hi:[1,0]
	v_pk_mul_f32 v[108:109], v[108:109], v[234:235] op_sel_hi:[1,0]
	v_cvt_pk_bf16_f32 v110, v110, v111
	v_cvt_pk_bf16_f32 v111, v112, v113
	v_cvt_pk_bf16_f32 v112, v106, v107
	v_cvt_pk_bf16_f32 v113, v108, v109
	ds_bpermute_b32 v106, v100, v110
	ds_bpermute_b32 v107, v100, v111
	ds_bpermute_b32 v108, v100, v112
	ds_bpermute_b32 v109, v100, v113
	s_waitcnt lgkmcnt(4)
	global_store_dwordx4 v152, v[122:125], s[2:3] nt
	v_add_u32_e32 v152, s0, v152
	v_fmamk_f32 v234, v238, 0x3a800000, v207
	v_rsq_f32_e32 v234, v234
	s_nop 0
	v_mul_f32_e32 v234, s36, v234
	v_pk_mul_f32 v[92:93], v[92:93], v[234:235] op_sel_hi:[1,0]
	v_pk_mul_f32 v[94:95], v[94:95], v[234:235] op_sel_hi:[1,0]
	v_pk_mul_f32 v[88:89], v[88:89], v[234:235] op_sel_hi:[1,0]
	v_pk_mul_f32 v[90:91], v[90:91], v[234:235] op_sel_hi:[1,0]
	v_cvt_pk_bf16_f32 v92, v92, v93
	v_cvt_pk_bf16_f32 v93, v94, v95
	v_cvt_pk_bf16_f32 v94, v88, v89
	v_cvt_pk_bf16_f32 v95, v90, v91
	ds_bpermute_b32 v88, v100, v92
	ds_bpermute_b32 v89, v100, v93
	ds_bpermute_b32 v90, v100, v94
	ds_bpermute_b32 v91, v100, v95
	s_waitcnt lgkmcnt(4)
	global_store_dwordx4 v152, v[106:109], s[2:3] nt
	v_add_u32_e32 v152, s0, v152
	v_fmamk_f32 v234, v239, 0x3a800000, v207
	v_rsq_f32_e32 v234, v234
	s_nop 0
	v_mul_f32_e32 v234, s36, v234
	v_pk_mul_f32 v[76:77], v[76:77], v[234:235] op_sel_hi:[1,0]
	v_pk_mul_f32 v[78:79], v[78:79], v[234:235] op_sel_hi:[1,0]
	v_pk_mul_f32 v[72:73], v[72:73], v[234:235] op_sel_hi:[1,0]
	v_pk_mul_f32 v[74:75], v[74:75], v[234:235] op_sel_hi:[1,0]
	v_cvt_pk_bf16_f32 v76, v76, v77
	v_cvt_pk_bf16_f32 v77, v78, v79
	v_cvt_pk_bf16_f32 v78, v72, v73
	v_cvt_pk_bf16_f32 v79, v74, v75
	ds_bpermute_b32 v72, v100, v76
	ds_bpermute_b32 v73, v100, v77
	ds_bpermute_b32 v74, v100, v78
	ds_bpermute_b32 v75, v100, v79
	s_waitcnt lgkmcnt(4)
	global_store_dwordx4 v152, v[88:91], s[2:3] nt
	v_add_u32_e32 v152, s0, v152
	s_waitcnt lgkmcnt(0)
	global_store_dwordx4 v152, v[72:75], s[2:3] nt
	s_waitcnt vmcnt(12)
	s_waitcnt lgkmcnt(0)
	s_barrier
	s_setprio 1
	s_waitcnt lgkmcnt(0)
	v_mfma_f32_16x16x32_bf16 v[126:129], v[144:147], v[182:185], 0
	v_add_u32_e32 v153, s32, v247
	v_fmamk_f32 v230, v236, 0x3a800000, v207
	v_rsq_f32_e32 v230, v230
	s_nop 0
	v_mfma_f32_16x16x32_bf16 v[122:125], v[158:161], v[182:185], 0
	v_mul_f32_e32 v230, s36, v230
	v_pk_mul_f32 v[118:119], v[118:119], v[230:231] op_sel_hi:[1,0]
	v_pk_mul_f32 v[120:121], v[120:121], v[230:231] op_sel_hi:[1,0]
	v_pk_mul_f32 v[114:115], v[114:115], v[230:231] op_sel_hi:[1,0]
	v_pk_mul_f32 v[116:117], v[116:117], v[230:231] op_sel_hi:[1,0]
	v_mfma_f32_16x16x32_bf16 v[110:113], v[144:147], v[190:193], 0
	v_cvt_pk_bf16_f32 v118, v118, v119
	v_cvt_pk_bf16_f32 v119, v120, v121
	v_cvt_pk_bf16_f32 v120, v114, v115
	v_cvt_pk_bf16_f32 v121, v116, v117
	ds_bpermute_b32 v114, v100, v118
	v_mfma_f32_16x16x32_bf16 v[106:109], v[158:161], v[190:193], 0
	ds_bpermute_b32 v115, v100, v119
	ds_bpermute_b32 v116, v100, v120
	ds_bpermute_b32 v117, v100, v121
	v_fmamk_f32 v230, v237, 0x3a800000, v207
	v_rsq_f32_e32 v230, v230
	v_mfma_f32_16x16x32_bf16 v[92:95], v[144:147], v[198:201], 0
	s_nop 0
	v_mul_f32_e32 v230, s36, v230
	v_pk_mul_f32 v[102:103], v[102:103], v[230:231] op_sel_hi:[1,0]
	v_pk_mul_f32 v[104:105], v[104:105], v[230:231] op_sel_hi:[1,0]
	v_mfma_f32_16x16x32_bf16 v[88:91], v[158:161], v[198:201], 0
	v_pk_mul_f32 v[96:97], v[96:97], v[230:231] op_sel_hi:[1,0]
	v_pk_mul_f32 v[98:99], v[98:99], v[230:231] op_sel_hi:[1,0]
	v_cvt_pk_bf16_f32 v102, v102, v103
	v_cvt_pk_bf16_f32 v103, v104, v105
	v_cvt_pk_bf16_f32 v104, v96, v97
	v_mfma_f32_16x16x32_bf16 v[76:79], v[144:147], v[208:211], 0
	v_cvt_pk_bf16_f32 v105, v98, v99
	ds_bpermute_b32 v96, v100, v102
	ds_bpermute_b32 v97, v100, v103
	ds_bpermute_b32 v98, v100, v104
	ds_bpermute_b32 v99, v100, v105
	v_mfma_f32_16x16x32_bf16 v[72:75], v[158:161], v[208:211], 0
	s_waitcnt lgkmcnt(4)
	global_store_dwordx4 v153, v[114:117], s[2:3] nt
	v_add_u32_e32 v153, s0, v153
	v_fmamk_f32 v230, v238, 0x3a800000, v207
	v_rsq_f32_e32 v230, v230
	v_mfma_f32_16x16x32_bf16 v[126:129], v[148:151], v[186:189], v[126:129]
	s_nop 0
	v_mul_f32_e32 v230, s36, v230
	v_pk_mul_f32 v[84:85], v[84:85], v[230:231] op_sel_hi:[1,0]
	v_pk_mul_f32 v[86:87], v[86:87], v[230:231] op_sel_hi:[1,0]
	v_mfma_f32_16x16x32_bf16 v[122:125], v[162:165], v[186:189], v[122:125]
	v_pk_mul_f32 v[80:81], v[80:81], v[230:231] op_sel_hi:[1,0]
	v_pk_mul_f32 v[82:83], v[82:83], v[230:231] op_sel_hi:[1,0]
	v_cvt_pk_bf16_f32 v84, v84, v85
	v_cvt_pk_bf16_f32 v85, v86, v87
	v_cvt_pk_bf16_f32 v86, v80, v81
	v_mfma_f32_16x16x32_bf16 v[110:113], v[148:151], v[194:197], v[110:113]
	v_cvt_pk_bf16_f32 v87, v82, v83
	ds_bpermute_b32 v80, v100, v84
	ds_bpermute_b32 v81, v100, v85
	ds_bpermute_b32 v82, v100, v86
	ds_bpermute_b32 v83, v100, v87
	v_mfma_f32_16x16x32_bf16 v[106:109], v[162:165], v[194:197], v[106:109]
	s_waitcnt lgkmcnt(4)
	global_store_dwordx4 v153, v[96:99], s[2:3] nt
	v_add_u32_e32 v153, s0, v153
	v_fmamk_f32 v230, v239, 0x3a800000, v207
	v_rsq_f32_e32 v230, v230
	v_mfma_f32_16x16x32_bf16 v[92:95], v[148:151], v[202:205], v[92:95]
	s_nop 0
	v_mul_f32_e32 v230, s36, v230
	v_pk_mul_f32 v[68:69], v[68:69], v[230:231] op_sel_hi:[1,0]
	v_pk_mul_f32 v[70:71], v[70:71], v[230:231] op_sel_hi:[1,0]
	v_mfma_f32_16x16x32_bf16 v[88:91], v[162:165], v[202:205], v[88:91]
	v_pk_mul_f32 v[64:65], v[64:65], v[230:231] op_sel_hi:[1,0]
	v_pk_mul_f32 v[66:67], v[66:67], v[230:231] op_sel_hi:[1,0]
	v_cvt_pk_bf16_f32 v68, v68, v69
	v_cvt_pk_bf16_f32 v69, v70, v71
	v_cvt_pk_bf16_f32 v70, v64, v65
	v_mfma_f32_16x16x32_bf16 v[76:79], v[148:151], v[226:229], v[76:79]
	v_cvt_pk_bf16_f32 v71, v66, v67
	ds_bpermute_b32 v64, v100, v68
	ds_bpermute_b32 v65, v100, v69
	ds_bpermute_b32 v66, v100, v70
	ds_bpermute_b32 v67, v100, v71
	v_mfma_f32_16x16x32_bf16 v[72:75], v[162:165], v[226:229], v[72:75]
	s_waitcnt lgkmcnt(4)
	global_store_dwordx4 v153, v[80:83], s[2:3] nt
	v_add_u32_e32 v153, s0, v153
	s_waitcnt lgkmcnt(0)
	global_store_dwordx4 v153, v[64:67], s[2:3] nt
	s_setprio 0
	s_setprio 1
	v_mfma_f32_16x16x32_bf16 v[118:121], v[166:169], v[182:185], 0
	v_mov_b32_e32 v152, v247
	v_fmamk_f32 v234, v240, 0x3a800000, v207
	v_rsq_f32_e32 v234, v234
	s_nop 0
	v_mfma_f32_16x16x32_bf16 v[114:117], v[174:177], v[182:185], 0
	v_mul_f32_e32 v234, s36, v234
	v_pk_mul_f32 v[60:61], v[60:61], v[234:235] op_sel_hi:[1,0]
	v_pk_mul_f32 v[62:63], v[62:63], v[234:235] op_sel_hi:[1,0]
	v_pk_mul_f32 v[56:57], v[56:57], v[234:235] op_sel_hi:[1,0]
	v_pk_mul_f32 v[58:59], v[58:59], v[234:235] op_sel_hi:[1,0]
	v_mfma_f32_16x16x32_bf16 v[102:105], v[166:169], v[190:193], 0
	v_cvt_pk_bf16_f32 v60, v60, v61
	v_cvt_pk_bf16_f32 v61, v62, v63
	v_cvt_pk_bf16_f32 v62, v56, v57
	v_cvt_pk_bf16_f32 v63, v58, v59
	ds_bpermute_b32 v56, v100, v60
	v_mfma_f32_16x16x32_bf16 v[96:99], v[174:177], v[190:193], 0
	ds_bpermute_b32 v57, v100, v61
	ds_bpermute_b32 v58, v100, v62
	ds_bpermute_b32 v59, v100, v63
	v_fmamk_f32 v234, v244, 0x3a800000, v207
	v_rsq_f32_e32 v234, v234
	v_mfma_f32_16x16x32_bf16 v[84:87], v[166:169], v[198:201], 0
	s_nop 0
	v_mul_f32_e32 v234, s36, v234
	v_pk_mul_f32 v[44:45], v[44:45], v[234:235] op_sel_hi:[1,0]
	v_pk_mul_f32 v[46:47], v[46:47], v[234:235] op_sel_hi:[1,0]
	v_mfma_f32_16x16x32_bf16 v[80:83], v[174:177], v[198:201], 0
	v_pk_mul_f32 v[40:41], v[40:41], v[234:235] op_sel_hi:[1,0]
	v_pk_mul_f32 v[42:43], v[42:43], v[234:235] op_sel_hi:[1,0]
	v_cvt_pk_bf16_f32 v44, v44, v45
	v_cvt_pk_bf16_f32 v45, v46, v47
	v_cvt_pk_bf16_f32 v46, v40, v41
	v_mfma_f32_16x16x32_bf16 v[68:71], v[166:169], v[208:211], 0
	v_cvt_pk_bf16_f32 v47, v42, v43
	ds_bpermute_b32 v40, v100, v44
	ds_bpermute_b32 v41, v100, v45
	ds_bpermute_b32 v42, v100, v46
	ds_bpermute_b32 v43, v100, v47
	v_mfma_f32_16x16x32_bf16 v[64:67], v[174:177], v[208:211], 0
	s_waitcnt lgkmcnt(4)
	global_store_dwordx4 v152, v[56:59], s[90:91] nt
	v_add_u32_e32 v152, s0, v152
	v_fmamk_f32 v234, v245, 0x3a800000, v207
	v_rsq_f32_e32 v234, v234
	v_mfma_f32_16x16x32_bf16 v[118:121], v[170:173], v[186:189], v[118:121]
	s_nop 0
	v_mul_f32_e32 v234, s36, v234
	v_pk_mul_f32 v[28:29], v[28:29], v[234:235] op_sel_hi:[1,0]
	v_pk_mul_f32 v[30:31], v[30:31], v[234:235] op_sel_hi:[1,0]
	v_mfma_f32_16x16x32_bf16 v[114:117], v[178:181], v[186:189], v[114:117]
	v_pk_mul_f32 v[24:25], v[24:25], v[234:235] op_sel_hi:[1,0]
	v_pk_mul_f32 v[26:27], v[26:27], v[234:235] op_sel_hi:[1,0]
	v_cvt_pk_bf16_f32 v28, v28, v29
	v_cvt_pk_bf16_f32 v29, v30, v31
	v_cvt_pk_bf16_f32 v30, v24, v25
	v_mfma_f32_16x16x32_bf16 v[102:105], v[170:173], v[194:197], v[102:105]
	v_cvt_pk_bf16_f32 v31, v26, v27
	ds_bpermute_b32 v24, v100, v28
	ds_bpermute_b32 v25, v100, v29
	ds_bpermute_b32 v26, v100, v30
	ds_bpermute_b32 v27, v100, v31
	v_mfma_f32_16x16x32_bf16 v[96:99], v[178:181], v[194:197], v[96:99]
	s_waitcnt lgkmcnt(4)
	global_store_dwordx4 v152, v[40:43], s[90:91] nt
	v_add_u32_e32 v152, s0, v152
	v_fmamk_f32 v234, v246, 0x3a800000, v207
	v_rsq_f32_e32 v234, v234
	v_mfma_f32_16x16x32_bf16 v[84:87], v[170:173], v[202:205], v[84:87]
	s_nop 0
	v_mul_f32_e32 v234, s36, v234
	v_pk_mul_f32 v[12:13], v[12:13], v[234:235] op_sel_hi:[1,0]
	v_pk_mul_f32 v[14:15], v[14:15], v[234:235] op_sel_hi:[1,0]
	v_mfma_f32_16x16x32_bf16 v[80:83], v[178:181], v[202:205], v[80:83]
	v_pk_mul_f32 v[8:9], v[8:9], v[234:235] op_sel_hi:[1,0]
	v_pk_mul_f32 v[10:11], v[10:11], v[234:235] op_sel_hi:[1,0]
	v_cvt_pk_bf16_f32 v12, v12, v13
	v_cvt_pk_bf16_f32 v13, v14, v15
	v_cvt_pk_bf16_f32 v14, v8, v9
	v_mfma_f32_16x16x32_bf16 v[68:71], v[170:173], v[226:229], v[68:71]
	v_cvt_pk_bf16_f32 v15, v10, v11
	ds_bpermute_b32 v8, v100, v12
	ds_bpermute_b32 v9, v100, v13
	ds_bpermute_b32 v10, v100, v14
	ds_bpermute_b32 v11, v100, v15
	v_mfma_f32_16x16x32_bf16 v[64:67], v[178:181], v[226:229], v[64:67]
	s_waitcnt lgkmcnt(4)
	global_store_dwordx4 v152, v[24:27], s[90:91] nt
	v_add_u32_e32 v152, s0, v152
	s_waitcnt lgkmcnt(0)
	global_store_dwordx4 v152, v[8:11], s[90:91] nt
	s_setprio 0
	s_barrier
	s_add_i32 s33, s33, s34
	v_lshl_add_u64 v[152:153], s[14:15], 0, v[132:133]
	s_mov_b32 m0, s33
	ds_read_b128 v[182:185], v156 offset:16384
	ds_read_b128 v[186:189], v156 offset:17408
	ds_read_b128 v[190:193], v156 offset:18432
	ds_read_b128 v[194:197], v156 offset:19456
	ds_read_b128 v[198:201], v156 offset:20480
	ds_read_b128 v[202:205], v156 offset:21504
	ds_read_b128 v[208:211], v156 offset:22528
	ds_read_b128 v[226:229], v156 offset:23552
	global_load_lds_dwordx4 v[152:153], off
	s_add_i32 m0, s33, 0x2000
	s_add_u32 s80, s14, 0x40000
	v_lshl_add_u64 v[212:213], s[14:15], 0, v[136:137]
	s_addc_u32 s81, s15, 0
	s_add_i32 s1, s1, s34
	global_load_lds_dwordx4 v[212:213], off
	v_lshl_add_u64 v[230:231], s[80:81], 0, v[132:133]
	s_mov_b32 m0, s1
	v_lshl_add_u64 v[232:233], s[28:29], 0, v[134:135]
	global_load_lds_dwordx4 v[230:231], off
	v_lshl_add_u64 v[230:231], s[80:81], 0, v[136:137]
	s_add_i32 m0, s1, 0x2000
	s_nop 0
	global_load_lds_dwordx4 v[230:231], off
	v_lshl_add_u64 v[230:231], s[28:29], 0, v[130:131]
	s_mov_b32 m0, s41
	s_nop 0
	global_load_lds_dwordx4 v[230:231], off
	s_mov_b32 m0, s60
	s_nop 0
	global_load_lds_dwordx4 v[232:233], off
	s_waitcnt vmcnt(20)
	s_waitcnt lgkmcnt(0)
	s_barrier
	s_setprio 1
	s_waitcnt lgkmcnt(0)
	v_mfma_f32_16x16x32_bf16 v[60:63], v[144:147], v[182:185], 0
	v_and_b32_e32 v100, 3, v224
	v_lshlrev_b32_e32 v100, 6, v100
	v_and_or_b32 v100, v224, 60, v100
	v_add_u32_e32 v236, s32, v247
	v_mfma_f32_16x16x32_bf16 v[56:59], v[158:161], v[182:185], 0
	v_fmamk_f32 v234, v240, 0x3a800000, v207
	v_rsq_f32_e32 v234, v234
	s_nop 0
	v_mul_f32_e32 v234, s36, v234
	v_pk_mul_f32 v[52:53], v[52:53], v[234:235] op_sel_hi:[1,0]
	v_mfma_f32_16x16x32_bf16 v[44:47], v[144:147], v[190:193], 0
	v_pk_mul_f32 v[54:55], v[54:55], v[234:235] op_sel_hi:[1,0]
	v_pk_mul_f32 v[48:49], v[48:49], v[234:235] op_sel_hi:[1,0]
	v_pk_mul_f32 v[50:51], v[50:51], v[234:235] op_sel_hi:[1,0]
	v_cvt_pk_bf16_f32 v52, v52, v53
	v_cvt_pk_bf16_f32 v53, v54, v55
	v_mfma_f32_16x16x32_bf16 v[40:43], v[158:161], v[190:193], 0
	v_cvt_pk_bf16_f32 v54, v48, v49
	v_cvt_pk_bf16_f32 v55, v50, v51
	ds_bpermute_b32 v48, v100, v52
	ds_bpermute_b32 v49, v100, v53
	ds_bpermute_b32 v50, v100, v54
	v_mfma_f32_16x16x32_bf16 v[28:31], v[144:147], v[198:201], 0
	ds_bpermute_b32 v51, v100, v55
	v_fmamk_f32 v234, v244, 0x3a800000, v207
	v_rsq_f32_e32 v234, v234
	s_nop 0
	v_mul_f32_e32 v234, s36, v234
	v_mfma_f32_16x16x32_bf16 v[24:27], v[158:161], v[198:201], 0
	v_pk_mul_f32 v[36:37], v[36:37], v[234:235] op_sel_hi:[1,0]
	v_pk_mul_f32 v[38:39], v[38:39], v[234:235] op_sel_hi:[1,0]
	v_pk_mul_f32 v[32:33], v[32:33], v[234:235] op_sel_hi:[1,0]
	v_pk_mul_f32 v[34:35], v[34:35], v[234:235] op_sel_hi:[1,0]
	v_cvt_pk_bf16_f32 v36, v36, v37
	v_mfma_f32_16x16x32_bf16 v[12:15], v[144:147], v[208:211], 0
	v_cvt_pk_bf16_f32 v37, v38, v39
	v_cvt_pk_bf16_f32 v38, v32, v33
	v_cvt_pk_bf16_f32 v39, v34, v35
	ds_bpermute_b32 v32, v100, v36
	ds_bpermute_b32 v33, v100, v37
	v_mfma_f32_16x16x32_bf16 v[8:11], v[158:161], v[208:211], 0
	ds_bpermute_b32 v34, v100, v38
	ds_bpermute_b32 v35, v100, v39
	s_waitcnt lgkmcnt(4)
	global_store_dwordx4 v236, v[48:51], s[90:91] nt
	v_add_u32_e32 v236, s0, v236
	v_mfma_f32_16x16x32_bf16 v[60:63], v[148:151], v[186:189], v[60:63]
	v_fmamk_f32 v234, v245, 0x3a800000, v207
	v_rsq_f32_e32 v234, v234
	s_nop 0
	v_mul_f32_e32 v234, s36, v234
	v_pk_mul_f32 v[20:21], v[20:21], v[234:235] op_sel_hi:[1,0]
	v_mfma_f32_16x16x32_bf16 v[56:59], v[162:165], v[186:189], v[56:59]
	v_pk_mul_f32 v[22:23], v[22:23], v[234:235] op_sel_hi:[1,0]
	v_pk_mul_f32 v[16:17], v[16:17], v[234:235] op_sel_hi:[1,0]
	v_pk_mul_f32 v[18:19], v[18:19], v[234:235] op_sel_hi:[1,0]
	v_cvt_pk_bf16_f32 v20, v20, v21
	v_cvt_pk_bf16_f32 v21, v22, v23
	v_mfma_f32_16x16x32_bf16 v[44:47], v[148:151], v[194:197], v[44:47]
	v_cvt_pk_bf16_f32 v22, v16, v17
	v_cvt_pk_bf16_f32 v23, v18, v19
	ds_bpermute_b32 v16, v100, v20
	ds_bpermute_b32 v17, v100, v21
	ds_bpermute_b32 v18, v100, v22
	v_mfma_f32_16x16x32_bf16 v[40:43], v[162:165], v[194:197], v[40:43]
	ds_bpermute_b32 v19, v100, v23
	s_waitcnt lgkmcnt(4)
	global_store_dwordx4 v236, v[32:35], s[90:91] nt
	v_add_u32_e32 v236, s0, v236
	v_fmamk_f32 v234, v246, 0x3a800000, v207
	v_mfma_f32_16x16x32_bf16 v[28:31], v[148:151], v[202:205], v[28:31]
	v_rsq_f32_e32 v234, v234
	s_nop 0
	v_mul_f32_e32 v234, s36, v234
	v_pk_mul_f32 v[4:5], v[4:5], v[234:235] op_sel_hi:[1,0]
	v_pk_mul_f32 v[6:7], v[6:7], v[234:235] op_sel_hi:[1,0]
	v_mfma_f32_16x16x32_bf16 v[24:27], v[162:165], v[202:205], v[24:27]
	v_pk_mul_f32 v[0:1], v[0:1], v[234:235] op_sel_hi:[1,0]
	v_pk_mul_f32 v[2:3], v[2:3], v[234:235] op_sel_hi:[1,0]
	v_cvt_pk_bf16_f32 v4, v4, v5
	v_cvt_pk_bf16_f32 v5, v6, v7
	v_cvt_pk_bf16_f32 v6, v0, v1
	v_mfma_f32_16x16x32_bf16 v[12:15], v[148:151], v[226:229], v[12:15]
	v_cvt_pk_bf16_f32 v7, v2, v3
	ds_bpermute_b32 v0, v100, v4
	ds_bpermute_b32 v1, v100, v5
	ds_bpermute_b32 v2, v100, v6
	ds_bpermute_b32 v3, v100, v7
	v_mfma_f32_16x16x32_bf16 v[8:11], v[162:165], v[226:229], v[8:11]
	s_waitcnt lgkmcnt(4)
	global_store_dwordx4 v236, v[16:19], s[90:91] nt
	v_add_u32_e32 v236, s0, v236
	s_waitcnt lgkmcnt(0)
	global_store_dwordx4 v236, v[0:3], s[90:91] nt
	s_setprio 0
	s_setprio 1
	v_mfma_f32_16x16x32_bf16 v[52:55], v[166:169], v[182:185], 0
	v_mfma_f32_16x16x32_bf16 v[48:51], v[174:177], v[182:185], 0
	v_mfma_f32_16x16x32_bf16 v[36:39], v[166:169], v[190:193], 0
	v_mfma_f32_16x16x32_bf16 v[32:35], v[174:177], v[190:193], 0
	v_mfma_f32_16x16x32_bf16 v[20:23], v[166:169], v[198:201], 0
	v_mfma_f32_16x16x32_bf16 v[16:19], v[174:177], v[198:201], 0
	v_mfma_f32_16x16x32_bf16 v[4:7], v[166:169], v[208:211], 0
	v_mfma_f32_16x16x32_bf16 v[0:3], v[174:177], v[208:211], 0
	v_mfma_f32_16x16x32_bf16 v[52:55], v[170:173], v[186:189], v[52:55]
	v_mfma_f32_16x16x32_bf16 v[48:51], v[178:181], v[186:189], v[48:51]
	v_mfma_f32_16x16x32_bf16 v[36:39], v[170:173], v[194:197], v[36:39]
	v_mfma_f32_16x16x32_bf16 v[32:35], v[178:181], v[194:197], v[32:35]
	v_mfma_f32_16x16x32_bf16 v[20:23], v[170:173], v[202:205], v[20:23]
	v_mfma_f32_16x16x32_bf16 v[16:19], v[178:181], v[202:205], v[16:19]
	v_mfma_f32_16x16x32_bf16 v[4:7], v[170:173], v[226:229], v[4:7]
	v_mfma_f32_16x16x32_bf16 v[0:3], v[178:181], v[226:229], v[0:3]
	s_setprio 0
	s_barrier
	s_add_i32 s1, 0, 0x18000
	v_add_u32_e32 v100, s1, v154
	s_add_i32 s33, 0, 0x1c000
	ds_read_b128 v[144:147], v100
	ds_read_b128 v[148:151], v100 offset:1024
	ds_read_b128 v[158:161], v100 offset:2048
	ds_read_b128 v[162:165], v100 offset:3072
	v_add_u32_e32 v100, s33, v154
	ds_read_b128 v[166:169], v100
	ds_read_b128 v[170:173], v100 offset:1024
	ds_read_b128 v[174:177], v100 offset:2048
	ds_read_b128 v[178:181], v100 offset:3072
	s_add_u32 s28, s28, 0x40000
	s_addc_u32 s29, s29, 0
	s_mov_b32 m0, s61
	v_lshl_add_u64 v[234:235], s[28:29], 0, v[130:131]
	ds_read_b128 v[182:185], v156 offset:32768
	ds_read_b128 v[186:189], v156 offset:33792
	ds_read_b128 v[190:193], v156 offset:34816
	ds_read_b128 v[194:197], v156 offset:35840
	ds_read_b128 v[198:201], v156 offset:36864
	ds_read_b128 v[202:205], v156 offset:37888
	ds_read_b128 v[208:211], v156 offset:38912
	ds_read_b128 v[226:229], v156 offset:39936
	global_load_lds_dwordx4 v[234:235], off
	v_lshl_add_u64 v[234:235], s[28:29], 0, v[134:135]
	s_mov_b32 m0, s69
	s_nop 0
	global_load_lds_dwordx4 v[234:235], off
	s_lshl_b32 s46, s40, 8
	s_add_i32 s46, s46, s84
	v_or_b32_e32 v100, s46, v139
	v_lshlrev_b32_e32 v100, 2, v100
	global_load_dword v236, v100, s[66:67]
	global_load_dword v237, v100, s[66:67] offset:64
	global_load_dword v238, v100, s[66:67] offset:128
	global_load_dword v239, v100, s[66:67] offset:192
	global_load_dword v240, v100, s[66:67] offset:512
	global_load_dword v244, v100, s[66:67] offset:576
	global_load_dword v245, v100, s[66:67] offset:640
	global_load_dword v246, v100, s[66:67] offset:704
	s_waitcnt vmcnt(32)
	s_waitcnt lgkmcnt(0)
	s_barrier
	s_setprio 1
	s_waitcnt lgkmcnt(0)
	v_mfma_f32_16x16x32_bf16 v[126:129], v[144:147], v[182:185], v[126:129]
	v_mfma_f32_16x16x32_bf16 v[122:125], v[158:161], v[182:185], v[122:125]
	v_mfma_f32_16x16x32_bf16 v[110:113], v[144:147], v[190:193], v[110:113]
	v_mfma_f32_16x16x32_bf16 v[106:109], v[158:161], v[190:193], v[106:109]
	v_mfma_f32_16x16x32_bf16 v[92:95], v[144:147], v[198:201], v[92:95]
	v_mfma_f32_16x16x32_bf16 v[88:91], v[158:161], v[198:201], v[88:91]
	v_mfma_f32_16x16x32_bf16 v[76:79], v[144:147], v[208:211], v[76:79]
	v_mfma_f32_16x16x32_bf16 v[72:75], v[158:161], v[208:211], v[72:75]
	v_mfma_f32_16x16x32_bf16 v[126:129], v[148:151], v[186:189], v[126:129]
	v_mfma_f32_16x16x32_bf16 v[122:125], v[162:165], v[186:189], v[122:125]
	v_mfma_f32_16x16x32_bf16 v[110:113], v[148:151], v[194:197], v[110:113]
	v_mfma_f32_16x16x32_bf16 v[106:109], v[162:165], v[194:197], v[106:109]
	v_mfma_f32_16x16x32_bf16 v[92:95], v[148:151], v[202:205], v[92:95]
	v_mfma_f32_16x16x32_bf16 v[88:91], v[162:165], v[202:205], v[88:91]
	v_mfma_f32_16x16x32_bf16 v[76:79], v[148:151], v[226:229], v[76:79]
	v_mfma_f32_16x16x32_bf16 v[72:75], v[162:165], v[226:229], v[72:75]
	s_setprio 0
	s_setprio 1
	v_mfma_f32_16x16x32_bf16 v[118:121], v[166:169], v[182:185], v[118:121]
	v_mfma_f32_16x16x32_bf16 v[114:117], v[174:177], v[182:185], v[114:117]
	v_mfma_f32_16x16x32_bf16 v[102:105], v[166:169], v[190:193], v[102:105]
	v_mfma_f32_16x16x32_bf16 v[96:99], v[174:177], v[190:193], v[96:99]
	v_mfma_f32_16x16x32_bf16 v[84:87], v[166:169], v[198:201], v[84:87]
	v_mfma_f32_16x16x32_bf16 v[80:83], v[174:177], v[198:201], v[80:83]
	v_mfma_f32_16x16x32_bf16 v[68:71], v[166:169], v[208:211], v[68:71]
	v_mfma_f32_16x16x32_bf16 v[64:67], v[174:177], v[208:211], v[64:67]
	v_mfma_f32_16x16x32_bf16 v[118:121], v[170:173], v[186:189], v[118:121]
	v_mfma_f32_16x16x32_bf16 v[114:117], v[178:181], v[186:189], v[114:117]
	v_mfma_f32_16x16x32_bf16 v[102:105], v[170:173], v[194:197], v[102:105]
	v_mfma_f32_16x16x32_bf16 v[96:99], v[178:181], v[194:197], v[96:99]
	v_mfma_f32_16x16x32_bf16 v[84:87], v[170:173], v[202:205], v[84:87]
	v_mfma_f32_16x16x32_bf16 v[80:83], v[178:181], v[202:205], v[80:83]
	v_mfma_f32_16x16x32_bf16 v[68:71], v[170:173], v[226:229], v[68:71]
	v_mfma_f32_16x16x32_bf16 v[64:67], v[178:181], v[226:229], v[64:67]
	s_setprio 0
	s_barrier
	s_add_i32 s1, s1, s34
	v_lshl_add_u64 v[152:153], v[152:153], 0, s[86:87]
	s_mov_b32 m0, s1
	ds_read_b128 v[182:185], v156 offset:49152
	ds_read_b128 v[186:189], v156 offset:50176
	ds_read_b128 v[190:193], v156 offset:51200
	ds_read_b128 v[194:197], v156 offset:52224
	ds_read_b128 v[198:201], v156 offset:53248
	ds_read_b128 v[202:205], v156 offset:54272
	ds_read_b128 v[208:211], v156 offset:55296
	ds_read_b128 v[226:229], v156 offset:56320
	global_load_lds_dwordx4 v[152:153], off
	s_add_i32 m0, s1, 0x2000
	s_add_u32 s14, s14, 0x40080
	v_lshl_add_u64 v[152:153], v[212:213], 0, s[86:87]
	s_addc_u32 s15, s15, 0
	s_add_i32 s1, s33, s34
	global_load_lds_dwordx4 v[152:153], off
	v_lshl_add_u64 v[152:153], s[14:15], 0, v[132:133]
	s_mov_b32 m0, s1
	s_nop 0
	global_load_lds_dwordx4 v[152:153], off
	v_lshl_add_u64 v[152:153], s[14:15], 0, v[136:137]
	s_add_i32 m0, s1, 0x2000
	s_nop 0
	global_load_lds_dwordx4 v[152:153], off
	v_lshl_add_u64 v[152:153], v[230:231], 0, s[86:87]
	s_mov_b32 m0, s89
	s_nop 0
	global_load_lds_dwordx4 v[152:153], off
	v_lshl_add_u64 v[152:153], v[232:233], 0, s[86:87]
	s_mov_b32 m0, s92
	s_nop 0
	global_load_lds_dwordx4 v[152:153], off
	s_waitcnt vmcnt(20)
	s_waitcnt lgkmcnt(0)
	s_barrier
	s_setprio 1
	s_waitcnt lgkmcnt(0)
	v_mfma_f32_16x16x32_bf16 v[60:63], v[144:147], v[182:185], v[60:63]
	v_mfma_f32_16x16x32_bf16 v[56:59], v[158:161], v[182:185], v[56:59]
	v_mfma_f32_16x16x32_bf16 v[44:47], v[144:147], v[190:193], v[44:47]
	v_mfma_f32_16x16x32_bf16 v[40:43], v[158:161], v[190:193], v[40:43]
	v_mfma_f32_16x16x32_bf16 v[28:31], v[144:147], v[198:201], v[28:31]
	v_mfma_f32_16x16x32_bf16 v[24:27], v[158:161], v[198:201], v[24:27]
	v_mfma_f32_16x16x32_bf16 v[12:15], v[144:147], v[208:211], v[12:15]
	v_mfma_f32_16x16x32_bf16 v[8:11], v[158:161], v[208:211], v[8:11]
	v_mfma_f32_16x16x32_bf16 v[60:63], v[148:151], v[186:189], v[60:63]
	v_mfma_f32_16x16x32_bf16 v[56:59], v[162:165], v[186:189], v[56:59]
	v_mfma_f32_16x16x32_bf16 v[44:47], v[148:151], v[194:197], v[44:47]
	v_mfma_f32_16x16x32_bf16 v[40:43], v[162:165], v[194:197], v[40:43]
	v_mfma_f32_16x16x32_bf16 v[28:31], v[148:151], v[202:205], v[28:31]
	v_mfma_f32_16x16x32_bf16 v[24:27], v[162:165], v[202:205], v[24:27]
	v_mfma_f32_16x16x32_bf16 v[12:15], v[148:151], v[226:229], v[12:15]
	v_mfma_f32_16x16x32_bf16 v[8:11], v[162:165], v[226:229], v[8:11]
	s_setprio 0
	s_setprio 1
	v_mfma_f32_16x16x32_bf16 v[52:55], v[166:169], v[182:185], v[52:55]
	v_mfma_f32_16x16x32_bf16 v[48:51], v[174:177], v[182:185], v[48:51]
	v_mfma_f32_16x16x32_bf16 v[36:39], v[166:169], v[190:193], v[36:39]
	v_mfma_f32_16x16x32_bf16 v[32:35], v[174:177], v[190:193], v[32:35]
	v_mfma_f32_16x16x32_bf16 v[20:23], v[166:169], v[198:201], v[20:23]
	v_mfma_f32_16x16x32_bf16 v[16:19], v[174:177], v[198:201], v[16:19]
	v_mfma_f32_16x16x32_bf16 v[4:7], v[166:169], v[208:211], v[4:7]
	v_mfma_f32_16x16x32_bf16 v[0:3], v[174:177], v[208:211], v[0:3]
	v_mfma_f32_16x16x32_bf16 v[52:55], v[170:173], v[186:189], v[52:55]
	v_mfma_f32_16x16x32_bf16 v[48:51], v[178:181], v[186:189], v[48:51]
	v_mfma_f32_16x16x32_bf16 v[36:39], v[170:173], v[194:197], v[36:39]
	v_mfma_f32_16x16x32_bf16 v[32:35], v[178:181], v[194:197], v[32:35]
	v_mfma_f32_16x16x32_bf16 v[20:23], v[170:173], v[202:205], v[20:23]
	v_mfma_f32_16x16x32_bf16 v[16:19], v[178:181], v[202:205], v[16:19]
	v_mfma_f32_16x16x32_bf16 v[4:7], v[170:173], v[226:229], v[4:7]
	v_mfma_f32_16x16x32_bf16 v[0:3], v[178:181], v[226:229], v[0:3]
	s_setprio 0
	s_barrier
	s_add_i32 s73, s73, 2
	s_add_u32 s12, s12, 0x100
	s_addc_u32 s13, s13, 0
	s_add_u32 s54, s54, 0x100
	s_addc_u32 s55, s55, 0
